# PH0: LayerNorm-constant sums (3 waves of workgroup 0, the phase's last arriver) with all 32 loads in flight instead of 16 round trips
# speedup vs baseline: 1.0046x; 1.0046x over previous
.LBB0_25:
	s_or_b64 exec, exec, s[0:1]
	s_cmp_lt_i32 s34, 3
	s_cbranch_scc0 .LBB0_33
	s_movk_i32 s0, 0x400
	v_mov_b32_e32 v1, 0
	v_cmp_gt_i32_e32 vcc, s0, v12
	v_mov_b32_e32 v0, v1
	v_mov_b32_e32 v3, v1
	v_mov_b32_e32 v2, v1
	v_mov_b32_e32 v8, v1
	s_and_saveexec_b64 s[0:1], vcc
	s_cbranch_execz .LBB0_30
	v_readlane_b32 s12, v255, 19
	s_cmp_eq_u32 s34, 1
	v_readlane_b32 s16, v255, 23
	v_readlane_b32 s17, v255, 24
	v_readlane_b32 s18, v255, 25
	v_readlane_b32 s19, v255, 26
	v_readlane_b32 s20, v255, 27
	v_readlane_b32 s21, v255, 28
	v_readlane_b32 s22, v255, 29
	v_readlane_b32 s23, v255, 30
	v_readlane_b32 s24, v255, 31
	v_readlane_b32 s25, v255, 32
	v_readlane_b32 s26, v255, 33
	v_readlane_b32 s27, v255, 34
	s_cselect_b32 s2, s36, s18
	s_cselect_b32 s3, s37, s19
	s_cselect_b32 s4, s38, s20
	s_cselect_b32 s5, s39, s21
	v_readlane_b32 s16, v255, 3
	v_readlane_b32 s13, v255, 20
	s_cmp_eq_u32 s34, 0
	v_readlane_b32 s30, v255, 17
	v_readlane_b32 s31, v255, 18
	v_ashrrev_i32_e32 v13, 31, v12
	s_cselect_b32 s3, s31, s3
	s_cselect_b32 s2, s30, s2
	s_cselect_b32 s5, s13, s5
	s_cselect_b32 s4, s12, s4
	v_lshlrev_b64 v[0:1], 2, v[12:13]
	v_mov_b32_e32 v8, 0
	v_subrev_u32_e32 v9, 64, v12
	v_lshl_add_u64 v[4:5], s[2:3], 0, v[0:1]
	v_lshl_add_u64 v[6:7], s[4:5], 0, v[0:1]
	s_mov_b64 s[2:3], 0
	s_mov_b64 s[4:5], 0x100
	s_movk_i32 s6, 0x3bf
	v_mov_b32_e32 v2, 0
	v_mov_b32_e32 v3, v8
	v_mov_b32_e32 v0, 0
	v_mov_b32_e32 v1, v8
	v_readlane_b32 s14, v255, 21
	v_readlane_b32 s15, v255, 22
	v_readlane_b32 s17, v255, 4
	v_readlane_b32 s18, v255, 5
	v_readlane_b32 s19, v255, 6
	v_readlane_b32 s20, v255, 7
	v_readlane_b32 s21, v255, 8
	v_readlane_b32 s22, v255, 9
	v_readlane_b32 s23, v255, 10
	v_readlane_b32 s24, v255, 11
	v_readlane_b32 s25, v255, 12
	v_readlane_b32 s26, v255, 13
	v_readlane_b32 s27, v255, 14
	v_readlane_b32 s28, v255, 15
	v_readlane_b32 s29, v255, 16
	global_load_dword v134, v[4:5], off offset:0
	global_load_dword v135, v[4:5], off offset:256
	global_load_dword v136, v[4:5], off offset:512
	global_load_dword v137, v[4:5], off offset:768
	global_load_dword v138, v[4:5], off offset:1024
	global_load_dword v139, v[4:5], off offset:1280
	global_load_dword v140, v[4:5], off offset:1536
	global_load_dword v141, v[4:5], off offset:1792
	global_load_dword v142, v[4:5], off offset:2048
	global_load_dword v143, v[4:5], off offset:2304
	global_load_dword v144, v[4:5], off offset:2560
	global_load_dword v145, v[4:5], off offset:2816
	global_load_dword v146, v[4:5], off offset:3072
	global_load_dword v147, v[4:5], off offset:3328
	global_load_dword v148, v[4:5], off offset:3584
	global_load_dword v149, v[4:5], off offset:3840
	global_load_dword v150, v[6:7], off offset:0
	global_load_dword v151, v[6:7], off offset:256
	global_load_dword v152, v[6:7], off offset:512
	global_load_dword v153, v[6:7], off offset:768
	global_load_dword v154, v[6:7], off offset:1024
	global_load_dword v155, v[6:7], off offset:1280
	global_load_dword v156, v[6:7], off offset:1536
	global_load_dword v157, v[6:7], off offset:1792
	global_load_dword v158, v[6:7], off offset:2048
	global_load_dword v159, v[6:7], off offset:2304
	global_load_dword v160, v[6:7], off offset:2560
	global_load_dword v161, v[6:7], off offset:2816
	global_load_dword v162, v[6:7], off offset:3072
	global_load_dword v163, v[6:7], off offset:3328
	global_load_dword v164, v[6:7], off offset:3584
	global_load_dword v165, v[6:7], off offset:3840
	s_waitcnt vmcnt(15)
	v_mul_f32_e32 v11, v134, v134
	v_mul_f32_e32 v16, v134, v150
	v_fmac_f32_e32 v8, v150, v150
	v_add_f32_e32 v2, v2, v134
	v_add_f32_e32 v3, v3, v11
	v_add_f32_e32 v0, v0, v16
	v_add_f32_e32 v1, v1, v150
	s_waitcnt vmcnt(14)
	v_mul_f32_e32 v11, v135, v135
	v_mul_f32_e32 v16, v135, v151
	v_fmac_f32_e32 v8, v151, v151
	v_add_f32_e32 v2, v2, v135
	v_add_f32_e32 v3, v3, v11
	v_add_f32_e32 v0, v0, v16
	v_add_f32_e32 v1, v1, v151
	s_waitcnt vmcnt(13)
	v_mul_f32_e32 v11, v136, v136
	v_mul_f32_e32 v16, v136, v152
	v_fmac_f32_e32 v8, v152, v152
	v_add_f32_e32 v2, v2, v136
	v_add_f32_e32 v3, v3, v11
	v_add_f32_e32 v0, v0, v16
	v_add_f32_e32 v1, v1, v152
	s_waitcnt vmcnt(12)
	v_mul_f32_e32 v11, v137, v137
	v_mul_f32_e32 v16, v137, v153
	v_fmac_f32_e32 v8, v153, v153
	v_add_f32_e32 v2, v2, v137
	v_add_f32_e32 v3, v3, v11
	v_add_f32_e32 v0, v0, v16
	v_add_f32_e32 v1, v1, v153
	s_waitcnt vmcnt(11)
	v_mul_f32_e32 v11, v138, v138
	v_mul_f32_e32 v16, v138, v154
	v_fmac_f32_e32 v8, v154, v154
	v_add_f32_e32 v2, v2, v138
	v_add_f32_e32 v3, v3, v11
	v_add_f32_e32 v0, v0, v16
	v_add_f32_e32 v1, v1, v154
	s_waitcnt vmcnt(10)
	v_mul_f32_e32 v11, v139, v139
	v_mul_f32_e32 v16, v139, v155
	v_fmac_f32_e32 v8, v155, v155
	v_add_f32_e32 v2, v2, v139
	v_add_f32_e32 v3, v3, v11
	v_add_f32_e32 v0, v0, v16
	v_add_f32_e32 v1, v1, v155
	s_waitcnt vmcnt(9)
	v_mul_f32_e32 v11, v140, v140
	v_mul_f32_e32 v16, v140, v156
	v_fmac_f32_e32 v8, v156, v156
	v_add_f32_e32 v2, v2, v140
	v_add_f32_e32 v3, v3, v11
	v_add_f32_e32 v0, v0, v16
	v_add_f32_e32 v1, v1, v156
	s_waitcnt vmcnt(8)
	v_mul_f32_e32 v11, v141, v141
	v_mul_f32_e32 v16, v141, v157
	v_fmac_f32_e32 v8, v157, v157
	v_add_f32_e32 v2, v2, v141
	v_add_f32_e32 v3, v3, v11
	v_add_f32_e32 v0, v0, v16
	v_add_f32_e32 v1, v1, v157
	s_waitcnt vmcnt(7)
	v_mul_f32_e32 v11, v142, v142
	v_mul_f32_e32 v16, v142, v158
	v_fmac_f32_e32 v8, v158, v158
	v_add_f32_e32 v2, v2, v142
	v_add_f32_e32 v3, v3, v11
	v_add_f32_e32 v0, v0, v16
	v_add_f32_e32 v1, v1, v158
	s_waitcnt vmcnt(6)
	v_mul_f32_e32 v11, v143, v143
	v_mul_f32_e32 v16, v143, v159
	v_fmac_f32_e32 v8, v159, v159
	v_add_f32_e32 v2, v2, v143
	v_add_f32_e32 v3, v3, v11
	v_add_f32_e32 v0, v0, v16
	v_add_f32_e32 v1, v1, v159
	s_waitcnt vmcnt(5)
	v_mul_f32_e32 v11, v144, v144
	v_mul_f32_e32 v16, v144, v160
	v_fmac_f32_e32 v8, v160, v160
	v_add_f32_e32 v2, v2, v144
	v_add_f32_e32 v3, v3, v11
	v_add_f32_e32 v0, v0, v16
	v_add_f32_e32 v1, v1, v160
	s_waitcnt vmcnt(4)
	v_mul_f32_e32 v11, v145, v145
	v_mul_f32_e32 v16, v145, v161
	v_fmac_f32_e32 v8, v161, v161
	v_add_f32_e32 v2, v2, v145
	v_add_f32_e32 v3, v3, v11
	v_add_f32_e32 v0, v0, v16
	v_add_f32_e32 v1, v1, v161
	s_waitcnt vmcnt(3)
	v_mul_f32_e32 v11, v146, v146
	v_mul_f32_e32 v16, v146, v162
	v_fmac_f32_e32 v8, v162, v162
	v_add_f32_e32 v2, v2, v146
	v_add_f32_e32 v3, v3, v11
	v_add_f32_e32 v0, v0, v16
	v_add_f32_e32 v1, v1, v162
	s_waitcnt vmcnt(2)
	v_mul_f32_e32 v11, v147, v147
	v_mul_f32_e32 v16, v147, v163
	v_fmac_f32_e32 v8, v163, v163
	v_add_f32_e32 v2, v2, v147
	v_add_f32_e32 v3, v3, v11
	v_add_f32_e32 v0, v0, v16
	v_add_f32_e32 v1, v1, v163
	s_waitcnt vmcnt(1)
	v_mul_f32_e32 v11, v148, v148
	v_mul_f32_e32 v16, v148, v164
	v_fmac_f32_e32 v8, v164, v164
	v_add_f32_e32 v2, v2, v148
	v_add_f32_e32 v3, v3, v11
	v_add_f32_e32 v0, v0, v16
	v_add_f32_e32 v1, v1, v164
	s_waitcnt vmcnt(0)
	v_mul_f32_e32 v11, v149, v149
	v_mul_f32_e32 v16, v149, v165
	v_fmac_f32_e32 v8, v165, v165
	v_add_f32_e32 v2, v2, v149
	v_add_f32_e32 v3, v3, v11
	v_add_f32_e32 v0, v0, v16
	v_add_f32_e32 v1, v1, v165
	s_or_b64 exec, exec, s[2:3]
